# B-unit (chunk MLP) output stage: issue all 16 U loads together, single wait, then 16 stores (was one load-wait-store round trip per row); on top of GEMM first-iteration peel and scalarized packed f32
# speedup vs baseline: 1.0173x; 1.0030x over previous
; #define LAS __attribute__((address_space(3)))
; __device__ __forceinline__ unsigned cvt_pk_bf16(float lo, float hi) { const f32x2 v = {lo, hi}; const bf16x2_t b = __builtin_convertvector(v, bf16x2_t); return __builtin_bit_cast(unsigned, b); }
; __device__ __forceinline__ void bmix_unit(LAS unsigned char* lds, const bf16_t* U, const bf16_t* VG, const float* gv  , const float* ws  , const float* bs  ,
;                                           int ci, int g, bf16_t* Y) {
;     ...
; #pragma unroll
;     for (int i = 0; i < 2; ++i) {
;         const int idx = tid + i * NTHREADS; const int q = idx >> 3, c8 = idx & 7;
;         const u32x4 w = *(const u32x4*)(VG + (size_t)(r0 + q) * 256 + g * 64 + c8 * 8); const float rs = rstd[q];
; #pragma unroll
;         for (int e = 0; e < 4; ++e) {
;             const float lo = __uint_as_float(w[e] << 16) * rs * gv[g * 64 + c8 * 8 + 2 * e], hi2 = __uint_as_float(w[e] & 0xffff0000u) * rs * gv[g * 64 + c8 * 8 + 2 * e + 1];
;             const unsigned pk = cvt_pk_bf16(lo, hi2);
;             vnT[(c8 * 8 + 2 * e) * 136 + q] = (bf16_t)(pk & 0xffffu); vnT[(c8 * 8 + 2 * e + 1) * 136 + q] = (bf16_t)(pk >> 16);
;         }
;     }
;     __syncthreads();
;     const int pblk = wid & 3, cblk = wid >> 2;
;     f32x16 acc;
; #pragma unroll
;     for (int r = 0; r < 16; ++r) acc[r] = 0.f;
;     const float* wrow = ws + ((size_t)g * 128 + pblk * 32 + r32) * 128 + hi * 8;
; #pragma unroll
;     for (int ks = 0; ks < 8; ++ks) {
;         const f32x4 a0 = *(const f32x4*)(wrow + ks * 16), a1 = *(const f32x4*)(wrow + ks * 16 + 4);
;         u32x4 aw; aw.x = cvt_pk_bf16(a0[0], a0[1]); aw.y = cvt_pk_bf16(a0[2], a0[3]); aw.z = cvt_pk_bf16(a1[0], a1[1]); aw.w = cvt_pk_bf16(a1[2], a1[3]);
;         const bf16x8 bfr = *(const LAS bf16x8*)(vnT + (cblk * 32 + r32) * 136 + ks * 16 + hi * 8);
;         acc = __builtin_amdgcn_mfma_f32_32x32x16_bf16(__builtin_bit_cast(bf16x8, aw), bfr, acc, 0, 0, 0);
;     }
.LBB0_592:
	s_or_b64 exec, exec, s[0:1]
	s_and_b32 s0, s56, 3
	s_lshl_b32 s1, s0, 6
	s_lshl_b32 s0, s0, 7
	v_readlane_b32 s8, v254, 31
	v_lshlrev_b32_e32 v0, 3, v16
	v_ashrrev_i32_e32 v19, 3, v16
	v_readlane_b32 s9, v254, 32
	s_add_u32 s8, s8, s0
	v_and_b32_e32 v15, 56, v0
	v_add_u32_e32 v0, s6, v19
	s_addc_u32 s9, s9, 0
	v_lshlrev_b32_e32 v194, 1, v15
	s_waitcnt lgkmcnt(0)
	v_ashrrev_i32_e32 v1, 31, v0
	v_lshl_add_u64 v[12:13], s[8:9], 0, v[194:195]
	v_lshlrev_b64 v[0:1], 9, v[0:1]
	v_lshl_add_u64 v[0:1], v[12:13], 0, v[0:1]
	s_barrier
	global_load_dwordx4 v[8:11], v[0:1], off
	v_lshl_add_u32 v0, v19, 2, 0
	ds_read_b32 v14, v0
	v_or_b32_e32 v2, s1, v15
	v_lshlrev_b32_e32 v4, 2, v2
	s_movk_i32 s10, 0x110
	s_lshr_b32 s8, s7, 1
	s_and_b32 s8, s8, 0x60
	v_and_b32_e32 v17, 31, v16
	s_or_b32 s9, s0, s8
	v_readlane_b32 s12, v255, 27
	v_bfe_u32 v18, v16, 5, 1
	v_readlane_b32 s13, v255, 28
	s_waitcnt vmcnt(0)
	v_lshlrev_b32_e32 v0, 16, v8
	v_and_b32_e32 v1, 0xffff0000, v8
	s_waitcnt lgkmcnt(0)
	v_mul_f32_e32 v20, v14, v0
	v_mul_f32_e32 v21, v14, v1
	global_load_dwordx4 v[0:3], v4, s[26:27] offset:16
	s_nop 0
	global_load_dwordx4 v[4:7], v4, s[26:27]
	s_waitcnt vmcnt(0)
	v_mul_f32_e32 v20, v4, v20
	v_mul_f32_e32 v21, v5, v21
	s_nop 0
	v_cvt_pk_bf16_f32 v8, v20, v21
	v_mad_u32_u24 v20, v15, s10, 0
	v_lshl_add_u32 v15, v19, 1, v20
	ds_write_b16 v15, v8 offset:512
	ds_write_b16_d16_hi v15, v8 offset:784
	v_lshlrev_b32_e32 v8, 16, v9
	v_and_b32_e32 v9, 0xffff0000, v9
	v_mul_f32_e32 v8, v14, v8
	v_mul_f32_e32 v9, v14, v9
	v_mul_f32_e32 v8, v8, v6
	v_mul_f32_e32 v9, v9, v7
	s_nop 0
	v_cvt_pk_bf16_f32 v8, v8, v9
	ds_write_b16 v15, v8 offset:1056
	ds_write_b16_d16_hi v15, v8 offset:1328
	v_lshlrev_b32_e32 v8, 16, v10
	v_and_b32_e32 v9, 0xffff0000, v10
	v_mul_f32_e32 v8, v14, v8
	v_mul_f32_e32 v9, v14, v9
	v_mul_f32_e32 v8, v8, v0
	v_mul_f32_e32 v9, v9, v1
	s_nop 0
	v_cvt_pk_bf16_f32 v8, v8, v9
	ds_write_b16 v15, v8 offset:1600
	ds_write_b16_d16_hi v15, v8 offset:1872
	v_lshlrev_b32_e32 v8, 16, v11
	v_and_b32_e32 v9, 0xffff0000, v11
	v_mul_f32_e32 v8, v14, v8
	v_mul_f32_e32 v9, v14, v9
	v_mul_f32_e32 v8, v8, v2
	v_mul_f32_e32 v9, v9, v3
	s_nop 0
	v_cvt_pk_bf16_f32 v8, v8, v9
	ds_write_b16 v15, v8 offset:2144
	ds_write_b16_d16_hi v15, v8 offset:2416
	v_add_u32_e32 v8, 0x200, v16
	v_ashrrev_i32_e32 v19, 3, v8
	v_add_u32_e32 v8, s6, v19
	v_ashrrev_i32_e32 v9, 31, v8
	v_lshlrev_b64 v[8:9], 9, v[8:9]
	v_lshl_add_u64 v[8:9], v[12:13], 0, v[8:9]
	global_load_dwordx4 v[8:11], v[8:9], off
	v_lshl_add_u32 v12, v19, 2, 0
	ds_read_b32 v12, v12
	s_waitcnt vmcnt(0)
	v_lshlrev_b32_e32 v14, 16, v8
	v_and_b32_e32 v15, 0xffff0000, v8
	s_waitcnt lgkmcnt(0)
	v_mul_f32_e32 v14, v12, v14
	v_mul_f32_e32 v15, v12, v15
	v_mul_f32_e32 v4, v4, v14
	v_mul_f32_e32 v5, v5, v15
	v_lshl_add_u32 v8, v19, 1, v20
	v_cvt_pk_bf16_f32 v4, v4, v5
	ds_write_b16 v8, v4 offset:512
	ds_write_b16_d16_hi v8, v4 offset:784
	v_lshlrev_b32_e32 v4, 16, v9
	v_and_b32_e32 v5, 0xffff0000, v9
	v_mul_f32_e32 v4, v12, v4
	v_mul_f32_e32 v5, v12, v5
	v_mul_f32_e32 v4, v6, v4
	v_mul_f32_e32 v5, v7, v5
	s_nop 0
	v_cvt_pk_bf16_f32 v4, v4, v5
	ds_write_b16 v8, v4 offset:1056
	ds_write_b16_d16_hi v8, v4 offset:1328
	v_lshlrev_b32_e32 v4, 16, v10
	v_and_b32_e32 v5, 0xffff0000, v10
	v_mul_f32_e32 v4, v12, v4
	v_mul_f32_e32 v5, v12, v5
	v_mul_f32_e32 v0, v0, v4
	v_mul_f32_e32 v1, v1, v5
	s_nop 0
	v_cvt_pk_bf16_f32 v0, v0, v1
	ds_write_b16 v8, v0 offset:1600
	ds_write_b16_d16_hi v8, v0 offset:1872
	v_lshlrev_b32_e32 v0, 16, v11
	v_and_b32_e32 v1, 0xffff0000, v11
	v_mul_f32_e32 v0, v12, v0
	v_mul_f32_e32 v1, v12, v1
	v_mul_f32_e32 v0, v2, v0
	v_mul_f32_e32 v1, v3, v1
	s_nop 0
	v_cvt_pk_bf16_f32 v0, v0, v1
	ds_write_b16 v8, v0 offset:2144
	ds_write_b16_d16_hi v8, v0 offset:2416
	v_or_b32_e32 v0, s9, v17
	v_lshlrev_b32_e32 v194, 9, v0
	v_lshl_add_u64 v[0:1], s[12:13], 0, v[194:195]
	v_lshlrev_b32_e32 v194, 5, v18
	s_ashr_i32 s9, s7, 3
	v_lshl_add_u64 v[32:33], v[0:1], 0, v[194:195]
	s_and_b32 s7, s9, 0xffffffe0
	v_mov_b32_e32 v0, s9
	s_movk_i32 s9, 0xffe0
	v_bfi_b32 v0, s9, v0, v16
	v_mul_lo_u32 v0, v0, s10
	v_lshlrev_b32_e32 v1, 4, v18
	s_waitcnt lgkmcnt(0)
	s_barrier
	v_add3_u32 v16, 0, v0, v1
	global_load_dwordx4 v[0:3], v[32:33], off offset:16
	global_load_dwordx4 v[4:7], v[32:33], off
	s_add_i32 s7, s7, s1
	s_waitcnt vmcnt(0)
	v_cvt_pk_bf16_f32 v4, v4, v5
	v_cvt_pk_bf16_f32 v5, v6, v7
	v_cvt_pk_bf16_f32 v6, v0, v1
	v_cvt_pk_bf16_f32 v7, v2, v3
	ds_read_b128 v[0:3], v16 offset:512
	ds_read_b128 v[20:23], v16 offset:544
	global_load_dwordx4 v[24:27], v[32:33], off offset:80
	global_load_dwordx4 v[28:31], v[32:33], off offset:64
	s_waitcnt lgkmcnt(1)
	v_mfma_f32_32x32x16_bf16 v[0:15], v[4:7], v[0:3], 0
	s_waitcnt vmcnt(0)
	v_cvt_pk_bf16_f32 v28, v28, v29
	v_cvt_pk_bf16_f32 v29, v30, v31
	v_cvt_pk_bf16_f32 v30, v24, v25
	v_cvt_pk_bf16_f32 v31, v26, v27
	s_waitcnt lgkmcnt(0)
	s_nop 0
	v_mfma_f32_32x32x16_bf16 v[0:15], v[28:31], v[20:23], v[0:15]
	global_load_dwordx4 v[20:23], v[32:33], off offset:144
	global_load_dwordx4 v[24:27], v[32:33], off offset:128
	s_waitcnt vmcnt(0)
	v_cvt_pk_bf16_f32 v24, v24, v25
	v_cvt_pk_bf16_f32 v25, v26, v27
	v_cvt_pk_bf16_f32 v26, v20, v21
	v_cvt_pk_bf16_f32 v27, v22, v23
	ds_read_b128 v[20:23], v16 offset:576
	s_waitcnt lgkmcnt(0)
	v_mfma_f32_32x32x16_bf16 v[0:15], v[24:27], v[20:23], v[0:15]
	global_load_dwordx4 v[20:23], v[32:33], off offset:208
	global_load_dwordx4 v[24:27], v[32:33], off offset:192
	s_waitcnt vmcnt(0)
	v_cvt_pk_bf16_f32 v24, v24, v25
	v_cvt_pk_bf16_f32 v25, v26, v27
	v_cvt_pk_bf16_f32 v26, v20, v21
	v_cvt_pk_bf16_f32 v27, v22, v23
	ds_read_b128 v[20:23], v16 offset:608
	s_waitcnt lgkmcnt(0)
; #define LAS __attribute__((address_space(3)))
; __device__ __forceinline__ unsigned cvt_pk_bf16(float lo, float hi) { const f32x2 v = {lo, hi}; const bf16x2_t b = __builtin_convertvector(v, bf16x2_t); return __builtin_bit_cast(unsigned, b); }
; __device__ __forceinline__ float bf2f(bf16_t v) { return __uint_as_float(((unsigned)v) << 16); }
; __device__ __forceinline__ int crow(int r, int hi) { return (r & 3) + 8 * (r >> 2) + 4 * hi; }
; __device__ __forceinline__ void bmix_unit(LAS unsigned char* lds, const bf16_t* U, const bf16_t* VG, const float* gv  , const float* ws  , const float* bs  ,
;                                           int ci, int g, bf16_t* Y) {
;     ...
;     for (int ks = 0; ks < 8; ++ks) {
;         const f32x4 a0 = *(const f32x4*)(wrow + ks * 16), a1 = *(const f32x4*)(wrow + ks * 16 + 4);
;         u32x4 aw; aw.x = cvt_pk_bf16(a0[0], a0[1]); aw.y = cvt_pk_bf16(a0[2], a0[3]); aw.z = cvt_pk_bf16(a1[0], a1[1]); aw.w = cvt_pk_bf16(a1[2], a1[3]);
;         const bf16x8 bfr = *(const LAS bf16x8*)(vnT + (cblk * 32 + r32) * 136 + ks * 16 + hi * 8);
;         acc = __builtin_amdgcn_mfma_f32_32x32x16_bf16(__builtin_bit_cast(bf16x8, aw), bfr, acc, 0, 0, 0);
;     }
; #pragma unroll
;     for (int r = 0; r < 16; ++r) {
;         const int p = pblk * 32 + crow(r, hi); const int col = g * 64 + cblk * 32 + r32;
;         const float mixed = acc[r] + bs[g * 128 + p];
;         const float uu = bf2f(U[(size_t)(r0 + p) * 256 + col]);
;         Y[(size_t)(r0 + p) * DM + 384 + col] = (bf16_t)(cvt_pk_bf16(uu * mixed, 0.f) & 0xffffu);
	v_mfma_f32_32x32x16_bf16 v[0:15], v[24:27], v[20:23], v[0:15]
	global_load_dwordx4 v[20:23], v[32:33], off offset:272
	global_load_dwordx4 v[24:27], v[32:33], off offset:256
	s_waitcnt vmcnt(0)
	v_cvt_pk_bf16_f32 v24, v24, v25
	v_cvt_pk_bf16_f32 v25, v26, v27
	v_cvt_pk_bf16_f32 v26, v20, v21
	v_cvt_pk_bf16_f32 v27, v22, v23
	ds_read_b128 v[20:23], v16 offset:640
	s_waitcnt lgkmcnt(0)
	v_mfma_f32_32x32x16_bf16 v[0:15], v[24:27], v[20:23], v[0:15]
	global_load_dwordx4 v[20:23], v[32:33], off offset:336
	global_load_dwordx4 v[24:27], v[32:33], off offset:320
	s_waitcnt vmcnt(0)
	v_cvt_pk_bf16_f32 v24, v24, v25
	v_cvt_pk_bf16_f32 v25, v26, v27
	v_cvt_pk_bf16_f32 v26, v20, v21
	v_cvt_pk_bf16_f32 v27, v22, v23
	ds_read_b128 v[20:23], v16 offset:672
	s_waitcnt lgkmcnt(0)
	v_mfma_f32_32x32x16_bf16 v[0:15], v[24:27], v[20:23], v[0:15]
	global_load_dwordx4 v[20:23], v[32:33], off offset:400
	global_load_dwordx4 v[24:27], v[32:33], off offset:384
	s_waitcnt vmcnt(0)
	v_cvt_pk_bf16_f32 v24, v24, v25
	v_cvt_pk_bf16_f32 v25, v26, v27
	v_cvt_pk_bf16_f32 v26, v20, v21
	v_cvt_pk_bf16_f32 v27, v22, v23
	ds_read_b128 v[20:23], v16 offset:704
	s_waitcnt lgkmcnt(0)
	v_mfma_f32_32x32x16_bf16 v[0:15], v[24:27], v[20:23], v[0:15]
	global_load_dwordx4 v[20:23], v[32:33], off offset:464
	global_load_dwordx4 v[24:27], v[32:33], off offset:448
	s_waitcnt vmcnt(0)
	v_cvt_pk_bf16_f32 v24, v24, v25
	v_cvt_pk_bf16_f32 v25, v26, v27
	v_cvt_pk_bf16_f32 v26, v20, v21
	v_cvt_pk_bf16_f32 v27, v22, v23
	ds_read_b128 v[20:23], v16 offset:736
	v_or_b32_e32 v16, s7, v17
	s_waitcnt lgkmcnt(0)
	v_mfma_f32_32x32x16_bf16 v[0:15], v[24:27], v[20:23], v[0:15]
	v_lshl_or_b32 v25, v18, 2, s8
	v_ashrrev_i32_e32 v17, 31, v16
	v_lshlrev_b64 v[20:21], 1, v[16:17]
	v_or_b32_e32 v16, s0, v25
	v_readlane_b32 s0, v255, 29
	v_lshlrev_b32_e32 v24, 2, v16
	v_readlane_b32 s1, v255, 30
	v_readlane_b32 s8, v254, 29
	v_readlane_b32 s9, v254, 30
	v_or_b32_e32 v194, s6, v25
	v_mov_b32_e32 v79, 0
	v_lshl_add_u64 v[22:23], s[8:9], 0, v[20:21]
	global_load_dwordx4 v[60:63], v24, s[0:1]
	global_load_dwordx4 v[64:67], v24, s[0:1] offset:32
	global_load_dwordx4 v[68:71], v24, s[0:1] offset:64
	global_load_dwordx4 v[72:75], v24, s[0:1] offset:96
	v_lshl_add_u64 v[76:77], s[86:87], 0, v[20:21]
	v_mov_b32_e32 v78, v194
	v_lshlrev_b64 v[80:81], 9, v[78:79]
	v_lshlrev_b64 v[82:83], 11, v[78:79]
	v_lshl_add_u64 v[80:81], v[22:23], 0, v[80:81]
	v_lshl_add_u64 v[100:101], v[76:77], 0, v[82:83]
	global_load_ushort v84, v[80:81], off
	v_or_b32_e32 v78, 1, v194
	v_lshlrev_b64 v[80:81], 9, v[78:79]
	v_lshlrev_b64 v[82:83], 11, v[78:79]
	v_lshl_add_u64 v[80:81], v[22:23], 0, v[80:81]
	v_lshl_add_u64 v[102:103], v[76:77], 0, v[82:83]
	global_load_ushort v85, v[80:81], off
	v_or_b32_e32 v78, 2, v194
	v_lshlrev_b64 v[80:81], 9, v[78:79]
	v_lshlrev_b64 v[82:83], 11, v[78:79]
	v_lshl_add_u64 v[80:81], v[22:23], 0, v[80:81]
	v_lshl_add_u64 v[104:105], v[76:77], 0, v[82:83]
	global_load_ushort v86, v[80:81], off
	v_or_b32_e32 v78, 3, v194
	v_lshlrev_b64 v[80:81], 9, v[78:79]
	v_lshlrev_b64 v[82:83], 11, v[78:79]
	v_lshl_add_u64 v[80:81], v[22:23], 0, v[80:81]
	v_lshl_add_u64 v[106:107], v[76:77], 0, v[82:83]
	global_load_ushort v87, v[80:81], off
	v_or_b32_e32 v78, 8, v194
	v_lshlrev_b64 v[80:81], 9, v[78:79]
	v_lshlrev_b64 v[82:83], 11, v[78:79]
	v_lshl_add_u64 v[80:81], v[22:23], 0, v[80:81]
	v_lshl_add_u64 v[108:109], v[76:77], 0, v[82:83]
	global_load_ushort v88, v[80:81], off
	v_or_b32_e32 v78, 9, v194
	v_lshlrev_b64 v[80:81], 9, v[78:79]
	v_lshlrev_b64 v[82:83], 11, v[78:79]
	v_lshl_add_u64 v[80:81], v[22:23], 0, v[80:81]
	v_lshl_add_u64 v[110:111], v[76:77], 0, v[82:83]
	global_load_ushort v89, v[80:81], off
	v_or_b32_e32 v78, 10, v194
	v_lshlrev_b64 v[80:81], 9, v[78:79]
	v_lshlrev_b64 v[82:83], 11, v[78:79]
	v_lshl_add_u64 v[80:81], v[22:23], 0, v[80:81]
	v_lshl_add_u64 v[112:113], v[76:77], 0, v[82:83]
	global_load_ushort v90, v[80:81], off
	v_or_b32_e32 v78, 11, v194
	v_lshlrev_b64 v[80:81], 9, v[78:79]
	v_lshlrev_b64 v[82:83], 11, v[78:79]
	v_lshl_add_u64 v[80:81], v[22:23], 0, v[80:81]
	v_lshl_add_u64 v[114:115], v[76:77], 0, v[82:83]
	global_load_ushort v91, v[80:81], off
	v_or_b32_e32 v78, 16, v194
	v_lshlrev_b64 v[80:81], 9, v[78:79]
	v_lshlrev_b64 v[82:83], 11, v[78:79]
	v_lshl_add_u64 v[80:81], v[22:23], 0, v[80:81]
	v_lshl_add_u64 v[116:117], v[76:77], 0, v[82:83]
	global_load_ushort v92, v[80:81], off
	v_or_b32_e32 v78, 17, v194
	v_lshlrev_b64 v[80:81], 9, v[78:79]
	v_lshlrev_b64 v[82:83], 11, v[78:79]
	v_lshl_add_u64 v[80:81], v[22:23], 0, v[80:81]
	v_lshl_add_u64 v[118:119], v[76:77], 0, v[82:83]
	global_load_ushort v93, v[80:81], off
	v_or_b32_e32 v78, 18, v194
	v_lshlrev_b64 v[80:81], 9, v[78:79]
	v_lshlrev_b64 v[82:83], 11, v[78:79]
	v_lshl_add_u64 v[80:81], v[22:23], 0, v[80:81]
	v_lshl_add_u64 v[120:121], v[76:77], 0, v[82:83]
	global_load_ushort v94, v[80:81], off
	v_or_b32_e32 v78, 19, v194
	v_lshlrev_b64 v[80:81], 9, v[78:79]
	v_lshlrev_b64 v[82:83], 11, v[78:79]
	v_lshl_add_u64 v[80:81], v[22:23], 0, v[80:81]
	v_lshl_add_u64 v[122:123], v[76:77], 0, v[82:83]
	global_load_ushort v95, v[80:81], off
	v_or_b32_e32 v78, 24, v194
	v_lshlrev_b64 v[80:81], 9, v[78:79]
	v_lshlrev_b64 v[82:83], 11, v[78:79]
	v_lshl_add_u64 v[80:81], v[22:23], 0, v[80:81]
	v_lshl_add_u64 v[124:125], v[76:77], 0, v[82:83]
	global_load_ushort v96, v[80:81], off
	v_or_b32_e32 v78, 25, v194
	v_lshlrev_b64 v[80:81], 9, v[78:79]
	v_lshlrev_b64 v[82:83], 11, v[78:79]
	v_lshl_add_u64 v[80:81], v[22:23], 0, v[80:81]
	v_lshl_add_u64 v[126:127], v[76:77], 0, v[82:83]
	global_load_ushort v97, v[80:81], off
	v_or_b32_e32 v78, 26, v194
	v_lshlrev_b64 v[80:81], 9, v[78:79]
	v_lshlrev_b64 v[82:83], 11, v[78:79]
	v_lshl_add_u64 v[80:81], v[22:23], 0, v[80:81]
	v_lshl_add_u64 v[128:129], v[76:77], 0, v[82:83]
	global_load_ushort v98, v[80:81], off
	v_or_b32_e32 v78, 27, v194
	v_lshlrev_b64 v[80:81], 9, v[78:79]
	v_lshlrev_b64 v[82:83], 11, v[78:79]
	v_lshl_add_u64 v[80:81], v[22:23], 0, v[80:81]
	v_lshl_add_u64 v[130:131], v[76:77], 0, v[82:83]
	global_load_ushort v99, v[80:81], off
	s_waitcnt vmcnt(0)
; __device__ __forceinline__ unsigned cvt_pk_bf16(float lo, float hi) { const f32x2 v = {lo, hi}; const bf16x2_t b = __builtin_convertvector(v, bf16x2_t); return __builtin_bit_cast(unsigned, b); }
; __device__ __forceinline__ float bf2f(bf16_t v) { return __uint_as_float(((unsigned)v) << 16); }
; __device__ __forceinline__ int crow(int r, int hi) { return (r & 3) + 8 * (r >> 2) + 4 * hi; }
; __device__ __forceinline__ void bmix_unit(LAS unsigned char* lds, const bf16_t* U, const bf16_t* VG, const float* gv  , const float* ws  , const float* bs  ,
;                                           int ci, int g, bf16_t* Y) {
;     ...
; #pragma unroll
;     for (int r = 0; r < 16; ++r) {
;         const int p = pblk * 32 + crow(r, hi); const int col = g * 64 + cblk * 32 + r32;
;         const float mixed = acc[r] + bs[g * 128 + p];
;         const float uu = bf2f(U[(size_t)(r0 + p) * 256 + col]);
;         Y[(size_t)(r0 + p) * DM + 384 + col] = (bf16_t)(cvt_pk_bf16(uu * mixed, 0.f) & 0xffffu);
;     }
;     __syncthreads();
	v_add_f32_e32 v132, v0, v60
	v_lshlrev_b32_e32 v84, 16, v84
	v_mul_f32_e32 v132, v132, v84
	v_cvt_pk_bf16_f32 v132, v132, v132
	global_store_short v[100:101], v132, off offset:768
	v_add_f32_e32 v133, v1, v61
	v_lshlrev_b32_e32 v85, 16, v85
	v_mul_f32_e32 v133, v133, v85
	v_cvt_pk_bf16_f32 v133, v133, v133
	global_store_short v[102:103], v133, off offset:768
	v_add_f32_e32 v134, v2, v62
	v_lshlrev_b32_e32 v86, 16, v86
	v_mul_f32_e32 v134, v134, v86
	v_cvt_pk_bf16_f32 v134, v134, v134
	global_store_short v[104:105], v134, off offset:768
	v_add_f32_e32 v135, v3, v63
	v_lshlrev_b32_e32 v87, 16, v87
	v_mul_f32_e32 v135, v135, v87
	v_cvt_pk_bf16_f32 v135, v135, v135
	global_store_short v[106:107], v135, off offset:768
	v_add_f32_e32 v136, v4, v64
	v_lshlrev_b32_e32 v88, 16, v88
	v_mul_f32_e32 v136, v136, v88
	v_cvt_pk_bf16_f32 v136, v136, v136
	global_store_short v[108:109], v136, off offset:768
	v_add_f32_e32 v137, v5, v65
	v_lshlrev_b32_e32 v89, 16, v89
	v_mul_f32_e32 v137, v137, v89
	v_cvt_pk_bf16_f32 v137, v137, v137
	global_store_short v[110:111], v137, off offset:768
	v_add_f32_e32 v138, v6, v66
	v_lshlrev_b32_e32 v90, 16, v90
	v_mul_f32_e32 v138, v138, v90
	v_cvt_pk_bf16_f32 v138, v138, v138
	global_store_short v[112:113], v138, off offset:768
	v_add_f32_e32 v139, v7, v67
	v_lshlrev_b32_e32 v91, 16, v91
	v_mul_f32_e32 v139, v139, v91
	v_cvt_pk_bf16_f32 v139, v139, v139
	global_store_short v[114:115], v139, off offset:768
	v_add_f32_e32 v140, v8, v68
	v_lshlrev_b32_e32 v92, 16, v92
	v_mul_f32_e32 v140, v140, v92
	v_cvt_pk_bf16_f32 v140, v140, v140
	global_store_short v[116:117], v140, off offset:768
	v_add_f32_e32 v141, v9, v69
	v_lshlrev_b32_e32 v93, 16, v93
	v_mul_f32_e32 v141, v141, v93
	v_cvt_pk_bf16_f32 v141, v141, v141
	global_store_short v[118:119], v141, off offset:768
	v_add_f32_e32 v142, v10, v70
	v_lshlrev_b32_e32 v94, 16, v94
	v_mul_f32_e32 v142, v142, v94
	v_cvt_pk_bf16_f32 v142, v142, v142
	global_store_short v[120:121], v142, off offset:768
	v_add_f32_e32 v143, v11, v71
	v_lshlrev_b32_e32 v95, 16, v95
	v_mul_f32_e32 v143, v143, v95
	v_cvt_pk_bf16_f32 v143, v143, v143
	global_store_short v[122:123], v143, off offset:768
	v_add_f32_e32 v144, v12, v72
	v_lshlrev_b32_e32 v96, 16, v96
	v_mul_f32_e32 v144, v144, v96
	v_cvt_pk_bf16_f32 v144, v144, v144
	global_store_short v[124:125], v144, off offset:768
	v_add_f32_e32 v145, v13, v73
	v_lshlrev_b32_e32 v97, 16, v97
	v_mul_f32_e32 v145, v145, v97
	v_cvt_pk_bf16_f32 v145, v145, v145
	global_store_short v[126:127], v145, off offset:768
	v_add_f32_e32 v146, v14, v74
	v_lshlrev_b32_e32 v98, 16, v98
	v_mul_f32_e32 v146, v146, v98
	v_cvt_pk_bf16_f32 v146, v146, v146
	global_store_short v[128:129], v146, off offset:768
	v_add_f32_e32 v147, v15, v75
	v_lshlrev_b32_e32 v99, 16, v99
	v_mul_f32_e32 v147, v147, v99
	v_cvt_pk_bf16_f32 v147, v147, v147
	global_store_short v[130:131], v147, off offset:768
	v_or_b32_e32 v194, 27, v194
	s_barrier
	s_mov_b64 s[0:1], 0
